# stagger: in layer 1 in_proj and gate_up, odd workgroups with one tile fewer start 4x s_sleep 127 later
# speedup vs baseline: 1.0052x; 1.0052x over previous
.LBB0_75:
	v_readlane_b32 s100, v253, 0
	s_movk_i32 s101, 0x7fff
	s_cmp_eq_u32 s63, 8
	s_cselect_b32 s101, 154, s101
	s_cmp_eq_u32 s63, 13
	s_cselect_b32 s101, 44, s101
	s_cmp_ge_u32 s100, s101
	s_cbranch_scc0 .Lstag_done
	s_bitcmp1_b32 s100, 0
	s_cbranch_scc0 .Lstag_done
	s_movk_i32 s101, 4
.Lstag_loop:
	s_sleep 127
	s_sub_i32 s101, s101, 1
	s_cmp_lg_u32 s101, 0
	s_cbranch_scc1 .Lstag_loop

	.amdhsa_kernel _Z8hymba_mk6Params
		.amdhsa_group_segment_fixed_size 0
		.amdhsa_private_segment_fixed_size 0
		.amdhsa_kernarg_size 448
		.amdhsa_user_sgpr_count 2
		.amdhsa_user_sgpr_dispatch_ptr 0
		.amdhsa_user_sgpr_queue_ptr 0
		.amdhsa_user_sgpr_kernarg_segment_ptr 1
		.amdhsa_user_sgpr_dispatch_id 0
		.amdhsa_user_sgpr_kernarg_preload_length 0
		.amdhsa_user_sgpr_kernarg_preload_offset 0
		.amdhsa_user_sgpr_private_segment_size 0
		.amdhsa_uses_dynamic_stack 0
		.amdhsa_enable_private_segment 0
		.amdhsa_system_sgpr_workgroup_id_x 1
		.amdhsa_system_sgpr_workgroup_id_y 0
		.amdhsa_system_sgpr_workgroup_id_z 0
		.amdhsa_system_sgpr_workgroup_info 0
		.amdhsa_system_vgpr_workitem_id 2
		.amdhsa_next_free_vgpr 256
		.amdhsa_next_free_sgpr 102
		.amdhsa_accum_offset 256
		.amdhsa_reserve_vcc 1
		.amdhsa_float_round_mode_32 0
		.amdhsa_float_round_mode_16_64 0
		.amdhsa_float_denorm_mode_32 3
		.amdhsa_float_denorm_mode_16_64 3
		.amdhsa_dx10_clamp 1
		.amdhsa_ieee_mode 1
		.amdhsa_fp16_overflow 0
		.amdhsa_tg_split 0
		.amdhsa_exception_fp_ieee_invalid_op 0
		.amdhsa_exception_fp_denorm_src 0
		.amdhsa_exception_fp_ieee_div_zero 0
		.amdhsa_exception_fp_ieee_overflow 0
		.amdhsa_exception_fp_ieee_underflow 0
		.amdhsa_exception_fp_ieee_inexact 0
		.amdhsa_exception_int_div_zero 0
	.end_amdhsa_kernel

amdhsa.kernels:
  - .agpr_count:     0
    .args:
      - .offset:         0
        .size:           192
        .value_kind:     by_value
      - .offset:         192
        .size:           4
        .value_kind:     hidden_block_count_x
      - .offset:         196
        .size:           4
        .value_kind:     hidden_block_count_y
      - .offset:         200
        .size:           4
        .value_kind:     hidden_block_count_z
      - .offset:         204
        .size:           2
        .value_kind:     hidden_group_size_x
      - .offset:         206
        .size:           2
        .value_kind:     hidden_group_size_y
      - .offset:         208
        .size:           2
        .value_kind:     hidden_group_size_z
      - .offset:         210
        .size:           2
        .value_kind:     hidden_remainder_x
      - .offset:         212
        .size:           2
        .value_kind:     hidden_remainder_y
      - .offset:         214
        .size:           2
        .value_kind:     hidden_remainder_z
      - .offset:         232
        .size:           8
        .value_kind:     hidden_global_offset_x
      - .offset:         240
        .size:           8
        .value_kind:     hidden_global_offset_y
      - .offset:         248
        .size:           8
        .value_kind:     hidden_global_offset_z
      - .offset:         256
        .size:           2
        .value_kind:     hidden_grid_dims
      - .offset:         280
        .size:           8
        .value_kind:     hidden_multigrid_sync_arg
      - .offset:         312
        .size:           4
        .value_kind:     hidden_dynamic_lds_size
    .group_segment_fixed_size: 0
    .kernarg_segment_align: 8
    .kernarg_segment_size: 448
    .language:       OpenCL C
    .language_version:
      - 2
      - 0
    .max_flat_workgroup_size: 512
    .name:           _Z8hymba_mk6Params
    .private_segment_fixed_size: 0
    .sgpr_count:     108
    .sgpr_spill_count: 177
    .symbol:         _Z8hymba_mk6Params.kd
    .uniform_work_group_size: 1
    .uses_dynamic_stack: false
    .vgpr_count:     256
    .vgpr_spill_count: 0
    .wavefront_size: 64
